# final combine-LN phase: nt (streaming) hint on the one-shot ys/h/partial row loads and the d_out stores
# speedup vs baseline: 1.0100x; 1.0073x over previous
; template <int SRC, int EXTRA, bool OUT8 = false> ...
;     ...
;     f32x4 gv[4], bv[4];
; #pragma unroll
;     for (int j = 0; j < 4; ++j) { gv[j] = *(const f32x4*)(g + 256 * j + 4 * lane); bv[j] = *(const f32x4*)(b + 256 * j + 4 * lane); }
;     const int gw = blockIdx.x * NWAVES + wave, NGW = G * NWAVES;
;     for (int row = gw; row < M; row += NGW) {
.LBB0_2243:
	s_or_b64 exec, exec, s[6:7]
	s_mov_b64 s[12:13], s[0:1]
	s_mov_b64 s[18:19], s[0:1]
	s_mov_b64 s[8:9], s[0:1]
	s_mov_b64 s[6:7], s[0:1]
	s_mov_b64 s[10:11], s[0:1]
	s_mov_b64 s[16:17], s[0:1]
	s_mov_b64 s[20:21], s[0:1]
	s_mov_b64 s[22:23], s[0:1]
	s_mov_b64 s[14:15], s[0:1]
	s_mov_b64 s[24:25], s[0:1]
	s_mov_b64 s[26:27], s[0:1]
	s_and_b64 vcc, exec, s[4:5]
	s_waitcnt lgkmcnt(0)
	s_barrier
	v_mbcnt_lo_u32_b32 v32, -1, 0
	v_mbcnt_hi_u32_b32 v32, -1, v32
	s_cbranch_vccnz .LBB0_2280
	s_load_dwordx2 s[4:5], s[24:25], 0xa8
	s_load_dwordx2 s[28:29], s[26:27], 0xb0
	v_lshlrev_b32_e32 v0, 4, v32
	v_mov_b32_e32 v113, 0
	v_and_b32_e32 v112, 0x3f0, v0
	s_waitcnt lgkmcnt(0)
	v_lshl_add_u64 v[0:1], s[4:5], 0, v[112:113]
	s_mov_b64 s[4:5], 0x1000
	s_movk_i32 s3, 0x1000
	v_lshl_add_u64 v[34:35], v[0:1], 0, s[4:5]
	v_add_co_u32_e32 v0, vcc, s3, v0
	v_lshl_add_u64 v[4:5], s[28:29], 0, v[112:113]
	s_nop 0
	v_addc_co_u32_e32 v1, vcc, 0, v1, vcc
	v_add_co_u32_e32 v38, vcc, s3, v4
	v_lshl_add_u64 v[36:37], v[4:5], 0, s[4:5]
	s_nop 0
	v_addc_co_u32_e32 v39, vcc, 0, v5, vcc
	global_load_dwordx4 v[0:3], v[0:1], off nt
	s_nop 0
	global_load_dwordx4 v[4:7], v[38:39], off nt
	global_load_dwordx4 v[8:11], v[34:35], off offset:1024 nt
	global_load_dwordx4 v[12:15], v[34:35], off offset:2048 nt
	global_load_dwordx4 v[16:19], v[36:37], off offset:1024 nt
	global_load_dwordx4 v[20:23], v[36:37], off offset:2048 nt
	global_load_dwordx4 v[24:27], v[34:35], off offset:3072 nt
	global_load_dwordx4 v[28:31], v[36:37], off offset:3072 nt
	s_load_dwordx2 s[24:25], s[18:19], 0xc0
	s_load_dwordx2 s[38:39], s[12:13], 0xc0
	s_nop 0
	s_load_dwordx2 s[12:13], s[8:9], 0x68
	s_load_dwordx2 s[18:19], s[16:17], 0xc0
	s_load_dwordx2 s[40:41], s[6:7], 0x70
	s_load_dwordx2 s[28:29], s[20:21], 0xc0
	s_load_dwordx2 s[42:43], s[10:11], 0xc0
	s_load_dwordx2 s[36:37], s[22:23], 0xc0
	s_nop 0
	s_load_dwordx2 s[6:7], s[14:15], 0xc0
	s_load_dwordx2 s[16:17], s[0:1], 0xb8
	s_waitcnt lgkmcnt(0)
	v_lshl_add_u64 v[34:35], s[12:13], 0, v[112:113]
	s_add_u32 s24, s24, 0x400000
	s_addc_u32 s25, s25, 0
	s_add_u32 s26, s18, 0x380000
	s_addc_u32 s27, s19, 0
	s_add_u32 s28, s28, 0x340000
	s_addc_u32 s29, s29, 0
	s_add_u32 s36, s36, 0x3c8000
	v_lshl_add_u64 v[114:115], v[34:35], 0, s[4:5]
	v_lshl_add_u64 v[34:35], s[40:41], 0, v[112:113]
	s_addc_u32 s37, s37, 0
	v_lshl_add_u64 v[116:117], v[34:35], 0, s[4:5]
	v_lshl_add_u64 v[34:35], s[6:7], 0, v[112:113]
	s_mov_b64 s[0:1], 0xe500000
	v_lshl_add_u64 v[118:119], v[34:35], 0, s[0:1]
	v_lshl_add_u64 v[34:35], s[42:43], 0, v[112:113]
	s_mov_b64 s[0:1], 0x2c500000
	s_cmp_lg_u64 s[16:17], 0
	v_lshl_add_u64 v[120:121], v[34:35], 0, s[0:1]
	s_cselect_b64 s[4:5], -1, 0
	s_lshl_b32 s0, s2, 4
	s_lshl_b32 s1, s68, 1
	s_ashr_i32 s35, s34, 31
	s_add_i32 s6, s0, s1
	s_lshl_b32 s15, s33, 4
	s_lshl_b64 s[0:1], s[34:35], 12
	s_add_u32 s8, s38, s0
	s_addc_u32 s9, s39, s1
	s_ashr_i32 s31, s30, 31
	s_lshl_b64 s[10:11], s[30:31], 12
	v_and_b32_e32 v32, 63, v32
	s_add_u32 s12, s16, s0
	s_mov_b32 s3, 0
	v_lshlrev_b32_e32 v112, 4, v32
	s_addc_u32 s13, s17, s1
	s_mov_b32 s31, 0x28500000
	s_mov_b32 s14, 0x3fb504f3
	v_mov_b32_e32 v126, 0x3727c5ac
	s_mov_b32 s33, 0xf800000
	v_mov_b32_e32 v127, 0x260
	s_branch .LBB0_2246

; template <int SRC, int EXTRA, bool OUT8 = false> ...
;     ...
;         } else {
;             const int p0 = pos[2 * row], p1 = pos[2 * row + 1]; const float w0 = gwt[2 * row], w1 = gwt[2 * row + 1]; const float hm = hp.stats[2 * row], hr = hp.stats[2 * row + 1];
; #pragma unroll
;             for (int j = 0; j < 4; ++j) { const f32x4 a = (*(const f32x4*)(hp.src + (size_t)row * 1024 + 256 * j + 4 * lane) - hm) * hr * *(const f32x4*)(hp.g + 256 * j + 4 * lane) + *(const f32x4*)(hp.b + 256 * j + 4 * lane);
;                 f32x4 y[2];
; #pragma unroll
;                 for (int q = 0; q < 2; ++q) { const int p = q ? p1 : p0; const int t = __builtin_amdgcn_readfirstlane(tailid[(p >> 8) * 4 + j]);
;                     if (t < 0) y[q] = *(const f32x4*)(ys + (size_t)p * 1024 + 256 * j + 4 * lane);
;                     else { f32x4 acc = (f32x4){0.f, 0.f, 0.f, 0.f};
; #pragma unroll
;                         for (int sl = 0; sl < 7; ++sl) acc = acc + *(const f32x4*)(part + ((size_t)(t * 7 + sl) * 256 + (p & 255)) * 256 + 4 * lane);
.LBB0_2246:
	s_ashr_i32 s7, s6, 31
	s_lshl_b64 s[0:1], s[6:7], 2
	s_add_u32 s16, s26, s0
	s_addc_u32 s17, s27, s1
	global_load_dwordx2 v[44:45], v113, s[16:17]
	s_add_u32 s20, s28, s0
	s_addc_u32 s21, s29, s1
	s_add_u32 s0, s24, s0
	s_addc_u32 s1, s25, s1
	global_load_dwordx2 v[124:125], v113, s[0:1]
	global_load_dwordx2 v[122:123], v113, s[20:21]
	v_lshl_add_u64 v[160:161], s[8:9], 0, v[112:113]
	v_add_co_u32_e32 v160, vcc, s31, v160
	s_nop 1
	v_addc_co_u32_e32 v161, vcc, 0, v161, vcc
	global_load_dwordx4 v[40:43], v[160:161], off nt
	global_load_dwordx4 v[60:63], v[160:161], off offset:1024 nt
	global_load_dwordx4 v[80:83], v[160:161], off offset:2048 nt
	global_load_dwordx4 v[100:103], v[160:161], off offset:3072 nt
	global_load_dwordx4 v[32:35], v[114:115], off nt
	global_load_dwordx4 v[52:55], v[114:115], off offset:1024 nt
	global_load_dwordx4 v[72:75], v[114:115], off offset:2048 nt
	global_load_dwordx4 v[88:91], v[114:115], off offset:3072 nt
	global_load_dwordx4 v[36:39], v[116:117], off nt
	global_load_dwordx4 v[56:59], v[116:117], off offset:1024 nt
	global_load_dwordx4 v[76:79], v[116:117], off offset:2048 nt
	global_load_dwordx4 v[92:95], v[116:117], off offset:3072 nt
	s_waitcnt vmcnt(14)
	v_readfirstlane_b32 s16, v44
	v_readfirstlane_b32 s22, v45
	s_ashr_i32 s0, s16, 6
	s_and_b32 s0, s0, -4
	s_ashr_i32 s1, s0, 31
	s_lshl_b64 s[0:1], s[0:1], 2
	s_add_u32 s18, s36, s0
	s_addc_u32 s19, s37, s1
	s_ashr_i32 s0, s22, 6
	s_and_b32 s0, s0, -4
	s_ashr_i32 s1, s0, 31
	s_lshl_b64 s[0:1], s[0:1], 2
	s_add_u32 s20, s36, s0
	s_addc_u32 s21, s37, s1
	global_load_dwordx4 v[168:171], v113, s[18:19]
	global_load_dwordx4 v[172:175], v113, s[20:21]
	s_ashr_i32 s17, s16, 31
	s_lshl_b64 s[0:1], s[16:17], 12
	v_lshl_add_u64 v[162:163], v[120:121], 0, s[0:1]
	s_ashr_i32 s23, s22, 31
	s_lshl_b64 s[0:1], s[22:23], 12
	v_lshl_add_u64 v[164:165], v[120:121], 0, s[0:1]
	global_load_dwordx4 v[44:47], v[162:163], off nt
	global_load_dwordx4 v[64:67], v[162:163], off offset:1024 nt
	global_load_dwordx4 v[84:87], v[162:163], off offset:2048 nt
	global_load_dwordx4 v[104:107], v[162:163], off offset:3072 nt
	global_load_dwordx4 v[48:51], v[164:165], off nt
	global_load_dwordx4 v[68:71], v[164:165], off offset:1024 nt
	global_load_dwordx4 v[96:99], v[164:165], off offset:2048 nt
	global_load_dwordx4 v[108:111], v[164:165], off offset:3072 nt
	s_waitcnt vmcnt(8)
	v_and_b32_e32 v176, v168, v169
	v_and_b32_e32 v177, v170, v171
	v_and_b32_e32 v178, v172, v173
	v_and_b32_e32 v179, v174, v175
	v_and_b32_e32 v176, v176, v177
	v_and_b32_e32 v178, v178, v179
	v_and_b32_e32 v176, v176, v178
	s_nop 0
	v_readfirstlane_b32 s0, v176
	s_waitcnt vmcnt(0)
	s_cmp_lt_i32 s0, 0
	s_cbranch_scc1 .LBB0_2278
	v_readfirstlane_b32 s1, v168
	s_cmp_lt_i32 s1, 0
	s_cbranch_scc1 .Lcomb_n00
	s_mul_i32 s20, s1, 7
	s_lshl_b32 s1, s16, 10
	s_and_b32 s2, s1, 0x3fc00
	s_mov_b32 s21, s3
	v_lshl_add_u64 v[176:177], v[118:119], 0, s[2:3]
	s_lshl_b64 s[38:39], s[20:21], 18
	v_lshl_add_u64 v[178:179], v[176:177], 0, s[38:39]
	global_load_dwordx4 v[128:131], v[178:179], off nt
	s_add_i32 s2, s20, 1
	s_lshl_b64 s[38:39], s[2:3], 18
	v_lshl_add_u64 v[182:183], v[176:177], 0, s[38:39]
	global_load_dwordx4 v[132:135], v[182:183], off nt
	s_add_i32 s2, s20, 2
	s_lshl_b64 s[38:39], s[2:3], 18
	v_lshl_add_u64 v[184:185], v[176:177], 0, s[38:39]
	global_load_dwordx4 v[136:139], v[184:185], off nt
	s_add_i32 s2, s20, 3
	s_lshl_b64 s[38:39], s[2:3], 18
	v_lshl_add_u64 v[186:187], v[176:177], 0, s[38:39]
	global_load_dwordx4 v[140:143], v[186:187], off nt
	s_add_i32 s2, s20, 4
	s_lshl_b64 s[38:39], s[2:3], 18
	v_lshl_add_u64 v[188:189], v[176:177], 0, s[38:39]
	global_load_dwordx4 v[144:147], v[188:189], off nt
	s_add_i32 s2, s20, 5
	s_lshl_b64 s[38:39], s[2:3], 18
	v_lshl_add_u64 v[190:191], v[176:177], 0, s[38:39]
	global_load_dwordx4 v[148:151], v[190:191], off nt
	s_add_i32 s2, s20, 6
	s_lshl_b64 s[38:39], s[2:3], 18
	v_lshl_add_u64 v[192:193], v[176:177], 0, s[38:39]
	global_load_dwordx4 v[152:155], v[192:193], off nt
	s_waitcnt vmcnt(6)
	v_pk_add_f32 v[46:47], v[130:131], 0 op_sel_hi:[1,0]
	v_pk_add_f32 v[44:45], v[128:129], 0 op_sel_hi:[1,0]
	s_waitcnt vmcnt(5)
	v_pk_add_f32 v[46:47], v[46:47], v[134:135]
	v_pk_add_f32 v[44:45], v[44:45], v[132:133]
	s_waitcnt vmcnt(4)
	v_pk_add_f32 v[46:47], v[46:47], v[138:139]
	v_pk_add_f32 v[44:45], v[44:45], v[136:137]
	s_waitcnt vmcnt(3)
	v_pk_add_f32 v[46:47], v[46:47], v[142:143]
	v_pk_add_f32 v[44:45], v[44:45], v[140:141]
	s_waitcnt vmcnt(2)
	v_pk_add_f32 v[46:47], v[46:47], v[146:147]
	v_pk_add_f32 v[44:45], v[44:45], v[144:145]
	s_waitcnt vmcnt(1)
	v_pk_add_f32 v[46:47], v[46:47], v[150:151]
	v_pk_add_f32 v[44:45], v[44:45], v[148:149]
	s_waitcnt vmcnt(0)
	v_pk_add_f32 v[46:47], v[46:47], v[154:155]
	v_pk_add_f32 v[44:45], v[44:45], v[152:153]
; template <int SRC, int EXTRA, bool OUT8 = false> ...
;     ...
;                 for (int q = 0; q < 2; ++q) { const int p = q ? p1 : p0; const int t = __builtin_amdgcn_readfirstlane(tailid[(p >> 8) * 4 + j]);
;                     if (t < 0) y[q] = *(const f32x4*)(ys + (size_t)p * 1024 + 256 * j + 4 * lane);
;                     else { f32x4 acc = (f32x4){0.f, 0.f, 0.f, 0.f};
; #pragma unroll
;                         for (int sl = 0; sl < 7; ++sl) acc = acc + *(const f32x4*)(part + ((size_t)(t * 7 + sl) * 256 + (p & 255)) * 256 + 4 * lane);
;                         y[q] = acc; } }
.Lcomb_n00:
	v_readfirstlane_b32 s1, v169
	s_cmp_lt_i32 s1, 0
	s_cbranch_scc1 .Lcomb_n01
	s_mul_i32 s20, s1, 7
	s_lshl_b32 s1, s16, 10
	s_and_b32 s2, s1, 0x3fc00
	s_mov_b32 s21, s3
	v_lshl_add_u64 v[176:177], v[118:119], 0, s[2:3]
	s_lshl_b64 s[38:39], s[20:21], 18
	v_lshl_add_u64 v[178:179], v[176:177], 0, s[38:39]
	global_load_dwordx4 v[128:131], v[178:179], off nt
	s_add_i32 s2, s20, 1
	s_lshl_b64 s[38:39], s[2:3], 18
	v_lshl_add_u64 v[182:183], v[176:177], 0, s[38:39]
	global_load_dwordx4 v[132:135], v[182:183], off nt
	s_add_i32 s2, s20, 2
	s_lshl_b64 s[38:39], s[2:3], 18
	v_lshl_add_u64 v[184:185], v[176:177], 0, s[38:39]
	global_load_dwordx4 v[136:139], v[184:185], off nt
	s_add_i32 s2, s20, 3
	s_lshl_b64 s[38:39], s[2:3], 18
	v_lshl_add_u64 v[186:187], v[176:177], 0, s[38:39]
	global_load_dwordx4 v[140:143], v[186:187], off nt
	s_add_i32 s2, s20, 4
	s_lshl_b64 s[38:39], s[2:3], 18
	v_lshl_add_u64 v[188:189], v[176:177], 0, s[38:39]
	global_load_dwordx4 v[144:147], v[188:189], off nt
	s_add_i32 s2, s20, 5
	s_lshl_b64 s[38:39], s[2:3], 18
	v_lshl_add_u64 v[190:191], v[176:177], 0, s[38:39]
	global_load_dwordx4 v[148:151], v[190:191], off nt
	s_add_i32 s2, s20, 6
	s_lshl_b64 s[38:39], s[2:3], 18
	v_lshl_add_u64 v[192:193], v[176:177], 0, s[38:39]
	global_load_dwordx4 v[152:155], v[192:193], off nt
	s_waitcnt vmcnt(6)
	v_pk_add_f32 v[66:67], v[130:131], 0 op_sel_hi:[1,0]
	v_pk_add_f32 v[64:65], v[128:129], 0 op_sel_hi:[1,0]
	s_waitcnt vmcnt(5)
	v_pk_add_f32 v[66:67], v[66:67], v[134:135]
	v_pk_add_f32 v[64:65], v[64:65], v[132:133]
	s_waitcnt vmcnt(4)
	v_pk_add_f32 v[66:67], v[66:67], v[138:139]
	v_pk_add_f32 v[64:65], v[64:65], v[136:137]
	s_waitcnt vmcnt(3)
	v_pk_add_f32 v[66:67], v[66:67], v[142:143]
	v_pk_add_f32 v[64:65], v[64:65], v[140:141]
	s_waitcnt vmcnt(2)
	v_pk_add_f32 v[66:67], v[66:67], v[146:147]
	v_pk_add_f32 v[64:65], v[64:65], v[144:145]
	s_waitcnt vmcnt(1)
	v_pk_add_f32 v[66:67], v[66:67], v[150:151]
	v_pk_add_f32 v[64:65], v[64:65], v[148:149]
	s_waitcnt vmcnt(0)
	v_pk_add_f32 v[66:67], v[66:67], v[154:155]
	v_pk_add_f32 v[64:65], v[64:65], v[152:153]
.Lcomb_n01:
	v_readfirstlane_b32 s1, v170
	s_cmp_lt_i32 s1, 0
	s_cbranch_scc1 .Lcomb_n02
	s_mul_i32 s20, s1, 7
	s_lshl_b32 s1, s16, 10
	s_and_b32 s2, s1, 0x3fc00
	s_mov_b32 s21, s3
	v_lshl_add_u64 v[176:177], v[118:119], 0, s[2:3]
	s_lshl_b64 s[38:39], s[20:21], 18
	v_lshl_add_u64 v[178:179], v[176:177], 0, s[38:39]
	global_load_dwordx4 v[128:131], v[178:179], off nt
	s_add_i32 s2, s20, 1
	s_lshl_b64 s[38:39], s[2:3], 18
	v_lshl_add_u64 v[182:183], v[176:177], 0, s[38:39]
	global_load_dwordx4 v[132:135], v[182:183], off nt
	s_add_i32 s2, s20, 2
	s_lshl_b64 s[38:39], s[2:3], 18
	v_lshl_add_u64 v[184:185], v[176:177], 0, s[38:39]
	global_load_dwordx4 v[136:139], v[184:185], off nt
	s_add_i32 s2, s20, 3
	s_lshl_b64 s[38:39], s[2:3], 18
	v_lshl_add_u64 v[186:187], v[176:177], 0, s[38:39]
	global_load_dwordx4 v[140:143], v[186:187], off nt
	s_add_i32 s2, s20, 4
	s_lshl_b64 s[38:39], s[2:3], 18
	v_lshl_add_u64 v[188:189], v[176:177], 0, s[38:39]
	global_load_dwordx4 v[144:147], v[188:189], off nt
	s_add_i32 s2, s20, 5
	s_lshl_b64 s[38:39], s[2:3], 18
	v_lshl_add_u64 v[190:191], v[176:177], 0, s[38:39]
	global_load_dwordx4 v[148:151], v[190:191], off nt
	s_add_i32 s2, s20, 6
	s_lshl_b64 s[38:39], s[2:3], 18
	v_lshl_add_u64 v[192:193], v[176:177], 0, s[38:39]
	global_load_dwordx4 v[152:155], v[192:193], off nt
	s_waitcnt vmcnt(6)
	v_pk_add_f32 v[86:87], v[130:131], 0 op_sel_hi:[1,0]
	v_pk_add_f32 v[84:85], v[128:129], 0 op_sel_hi:[1,0]
	s_waitcnt vmcnt(5)
	v_pk_add_f32 v[86:87], v[86:87], v[134:135]
	v_pk_add_f32 v[84:85], v[84:85], v[132:133]
	s_waitcnt vmcnt(4)
	v_pk_add_f32 v[86:87], v[86:87], v[138:139]
	v_pk_add_f32 v[84:85], v[84:85], v[136:137]
	s_waitcnt vmcnt(3)
	v_pk_add_f32 v[86:87], v[86:87], v[142:143]
	v_pk_add_f32 v[84:85], v[84:85], v[140:141]
	s_waitcnt vmcnt(2)
	v_pk_add_f32 v[86:87], v[86:87], v[146:147]
	v_pk_add_f32 v[84:85], v[84:85], v[144:145]
	s_waitcnt vmcnt(1)
	v_pk_add_f32 v[86:87], v[86:87], v[150:151]
	v_pk_add_f32 v[84:85], v[84:85], v[148:149]
	s_waitcnt vmcnt(0)
	v_pk_add_f32 v[86:87], v[86:87], v[154:155]
	v_pk_add_f32 v[84:85], v[84:85], v[152:153]
.Lcomb_n02:
	v_readfirstlane_b32 s1, v171
	s_cmp_lt_i32 s1, 0
	s_cbranch_scc1 .Lcomb_n03
	s_mul_i32 s20, s1, 7
	s_lshl_b32 s1, s16, 10
	s_and_b32 s2, s1, 0x3fc00
	s_mov_b32 s21, s3
	v_lshl_add_u64 v[176:177], v[118:119], 0, s[2:3]
	s_lshl_b64 s[38:39], s[20:21], 18
	v_lshl_add_u64 v[178:179], v[176:177], 0, s[38:39]
	global_load_dwordx4 v[128:131], v[178:179], off nt
	s_add_i32 s2, s20, 1
	s_lshl_b64 s[38:39], s[2:3], 18
	v_lshl_add_u64 v[182:183], v[176:177], 0, s[38:39]
	global_load_dwordx4 v[132:135], v[182:183], off nt
	s_add_i32 s2, s20, 2
	s_lshl_b64 s[38:39], s[2:3], 18
	v_lshl_add_u64 v[184:185], v[176:177], 0, s[38:39]
	global_load_dwordx4 v[136:139], v[184:185], off nt
	s_add_i32 s2, s20, 3
	s_lshl_b64 s[38:39], s[2:3], 18
	v_lshl_add_u64 v[186:187], v[176:177], 0, s[38:39]
	global_load_dwordx4 v[140:143], v[186:187], off nt
	s_add_i32 s2, s20, 4
	s_lshl_b64 s[38:39], s[2:3], 18
	v_lshl_add_u64 v[188:189], v[176:177], 0, s[38:39]
	global_load_dwordx4 v[144:147], v[188:189], off nt
	s_add_i32 s2, s20, 5
	s_lshl_b64 s[38:39], s[2:3], 18
	v_lshl_add_u64 v[190:191], v[176:177], 0, s[38:39]
	global_load_dwordx4 v[148:151], v[190:191], off nt
	s_add_i32 s2, s20, 6
	s_lshl_b64 s[38:39], s[2:3], 18
	v_lshl_add_u64 v[192:193], v[176:177], 0, s[38:39]
	global_load_dwordx4 v[152:155], v[192:193], off nt
	s_waitcnt vmcnt(6)
	v_pk_add_f32 v[106:107], v[130:131], 0 op_sel_hi:[1,0]
	v_pk_add_f32 v[104:105], v[128:129], 0 op_sel_hi:[1,0]
	s_waitcnt vmcnt(5)
	v_pk_add_f32 v[106:107], v[106:107], v[134:135]
	v_pk_add_f32 v[104:105], v[104:105], v[132:133]
	s_waitcnt vmcnt(4)
	v_pk_add_f32 v[106:107], v[106:107], v[138:139]
	v_pk_add_f32 v[104:105], v[104:105], v[136:137]
	s_waitcnt vmcnt(3)
	v_pk_add_f32 v[106:107], v[106:107], v[142:143]
	v_pk_add_f32 v[104:105], v[104:105], v[140:141]
	s_waitcnt vmcnt(2)
	v_pk_add_f32 v[106:107], v[106:107], v[146:147]
	v_pk_add_f32 v[104:105], v[104:105], v[144:145]
	s_waitcnt vmcnt(1)
	v_pk_add_f32 v[106:107], v[106:107], v[150:151]
	v_pk_add_f32 v[104:105], v[104:105], v[148:149]
	s_waitcnt vmcnt(0)
	v_pk_add_f32 v[106:107], v[106:107], v[154:155]
	v_pk_add_f32 v[104:105], v[104:105], v[152:153]
; template <int SRC, int EXTRA, bool OUT8 = false> ...
;     ...
;                 for (int q = 0; q < 2; ++q) { const int p = q ? p1 : p0; const int t = __builtin_amdgcn_readfirstlane(tailid[(p >> 8) * 4 + j]);
;                     if (t < 0) y[q] = *(const f32x4*)(ys + (size_t)p * 1024 + 256 * j + 4 * lane);
;                     else { f32x4 acc = (f32x4){0.f, 0.f, 0.f, 0.f};
; #pragma unroll
;                         for (int sl = 0; sl < 7; ++sl) acc = acc + *(const f32x4*)(part + ((size_t)(t * 7 + sl) * 256 + (p & 255)) * 256 + 4 * lane);
;                         y[q] = acc; } }
.Lcomb_n03:
	v_readfirstlane_b32 s1, v172
	s_cmp_lt_i32 s1, 0
	s_cbranch_scc1 .Lcomb_n10
	s_mul_i32 s20, s1, 7
	s_lshl_b32 s1, s22, 10
	s_and_b32 s2, s1, 0x3fc00
	s_mov_b32 s21, s3
	v_lshl_add_u64 v[176:177], v[118:119], 0, s[2:3]
	s_lshl_b64 s[38:39], s[20:21], 18
	v_lshl_add_u64 v[178:179], v[176:177], 0, s[38:39]
	global_load_dwordx4 v[128:131], v[178:179], off nt
	s_add_i32 s2, s20, 1
	s_lshl_b64 s[38:39], s[2:3], 18
	v_lshl_add_u64 v[182:183], v[176:177], 0, s[38:39]
	global_load_dwordx4 v[132:135], v[182:183], off nt
	s_add_i32 s2, s20, 2
	s_lshl_b64 s[38:39], s[2:3], 18
	v_lshl_add_u64 v[184:185], v[176:177], 0, s[38:39]
	global_load_dwordx4 v[136:139], v[184:185], off nt
	s_add_i32 s2, s20, 3
	s_lshl_b64 s[38:39], s[2:3], 18
	v_lshl_add_u64 v[186:187], v[176:177], 0, s[38:39]
	global_load_dwordx4 v[140:143], v[186:187], off nt
	s_add_i32 s2, s20, 4
	s_lshl_b64 s[38:39], s[2:3], 18
	v_lshl_add_u64 v[188:189], v[176:177], 0, s[38:39]
	global_load_dwordx4 v[144:147], v[188:189], off nt
	s_add_i32 s2, s20, 5
	s_lshl_b64 s[38:39], s[2:3], 18
	v_lshl_add_u64 v[190:191], v[176:177], 0, s[38:39]
	global_load_dwordx4 v[148:151], v[190:191], off nt
	s_add_i32 s2, s20, 6
	s_lshl_b64 s[38:39], s[2:3], 18
	v_lshl_add_u64 v[192:193], v[176:177], 0, s[38:39]
	global_load_dwordx4 v[152:155], v[192:193], off nt
	s_waitcnt vmcnt(6)
	v_pk_add_f32 v[50:51], v[130:131], 0 op_sel_hi:[1,0]
	v_pk_add_f32 v[48:49], v[128:129], 0 op_sel_hi:[1,0]
	s_waitcnt vmcnt(5)
	v_pk_add_f32 v[50:51], v[50:51], v[134:135]
	v_pk_add_f32 v[48:49], v[48:49], v[132:133]
	s_waitcnt vmcnt(4)
	v_pk_add_f32 v[50:51], v[50:51], v[138:139]
	v_pk_add_f32 v[48:49], v[48:49], v[136:137]
	s_waitcnt vmcnt(3)
	v_pk_add_f32 v[50:51], v[50:51], v[142:143]
	v_pk_add_f32 v[48:49], v[48:49], v[140:141]
	s_waitcnt vmcnt(2)
	v_pk_add_f32 v[50:51], v[50:51], v[146:147]
	v_pk_add_f32 v[48:49], v[48:49], v[144:145]
	s_waitcnt vmcnt(1)
	v_pk_add_f32 v[50:51], v[50:51], v[150:151]
	v_pk_add_f32 v[48:49], v[48:49], v[148:149]
	s_waitcnt vmcnt(0)
	v_pk_add_f32 v[50:51], v[50:51], v[154:155]
	v_pk_add_f32 v[48:49], v[48:49], v[152:153]
.Lcomb_n10:
	v_readfirstlane_b32 s1, v173
	s_cmp_lt_i32 s1, 0
	s_cbranch_scc1 .Lcomb_n11
	s_mul_i32 s20, s1, 7
	s_lshl_b32 s1, s22, 10
	s_and_b32 s2, s1, 0x3fc00
	s_mov_b32 s21, s3
	v_lshl_add_u64 v[176:177], v[118:119], 0, s[2:3]
	s_lshl_b64 s[38:39], s[20:21], 18
	v_lshl_add_u64 v[178:179], v[176:177], 0, s[38:39]
	global_load_dwordx4 v[128:131], v[178:179], off nt
	s_add_i32 s2, s20, 1
	s_lshl_b64 s[38:39], s[2:3], 18
	v_lshl_add_u64 v[182:183], v[176:177], 0, s[38:39]
	global_load_dwordx4 v[132:135], v[182:183], off nt
	s_add_i32 s2, s20, 2
	s_lshl_b64 s[38:39], s[2:3], 18
	v_lshl_add_u64 v[184:185], v[176:177], 0, s[38:39]
	global_load_dwordx4 v[136:139], v[184:185], off nt
	s_add_i32 s2, s20, 3
	s_lshl_b64 s[38:39], s[2:3], 18
	v_lshl_add_u64 v[186:187], v[176:177], 0, s[38:39]
	global_load_dwordx4 v[140:143], v[186:187], off nt
	s_add_i32 s2, s20, 4
	s_lshl_b64 s[38:39], s[2:3], 18
	v_lshl_add_u64 v[188:189], v[176:177], 0, s[38:39]
	global_load_dwordx4 v[144:147], v[188:189], off nt
	s_add_i32 s2, s20, 5
	s_lshl_b64 s[38:39], s[2:3], 18
	v_lshl_add_u64 v[190:191], v[176:177], 0, s[38:39]
	global_load_dwordx4 v[148:151], v[190:191], off nt
	s_add_i32 s2, s20, 6
	s_lshl_b64 s[38:39], s[2:3], 18
	v_lshl_add_u64 v[192:193], v[176:177], 0, s[38:39]
	global_load_dwordx4 v[152:155], v[192:193], off nt
	s_waitcnt vmcnt(6)
	v_pk_add_f32 v[70:71], v[130:131], 0 op_sel_hi:[1,0]
	v_pk_add_f32 v[68:69], v[128:129], 0 op_sel_hi:[1,0]
	s_waitcnt vmcnt(5)
	v_pk_add_f32 v[70:71], v[70:71], v[134:135]
	v_pk_add_f32 v[68:69], v[68:69], v[132:133]
	s_waitcnt vmcnt(4)
	v_pk_add_f32 v[70:71], v[70:71], v[138:139]
	v_pk_add_f32 v[68:69], v[68:69], v[136:137]
	s_waitcnt vmcnt(3)
	v_pk_add_f32 v[70:71], v[70:71], v[142:143]
	v_pk_add_f32 v[68:69], v[68:69], v[140:141]
	s_waitcnt vmcnt(2)
	v_pk_add_f32 v[70:71], v[70:71], v[146:147]
	v_pk_add_f32 v[68:69], v[68:69], v[144:145]
	s_waitcnt vmcnt(1)
	v_pk_add_f32 v[70:71], v[70:71], v[150:151]
	v_pk_add_f32 v[68:69], v[68:69], v[148:149]
	s_waitcnt vmcnt(0)
	v_pk_add_f32 v[70:71], v[70:71], v[154:155]
	v_pk_add_f32 v[68:69], v[68:69], v[152:153]
.Lcomb_n11:
	v_readfirstlane_b32 s1, v174
	s_cmp_lt_i32 s1, 0
	s_cbranch_scc1 .Lcomb_n12
	s_mul_i32 s20, s1, 7
	s_lshl_b32 s1, s22, 10
	s_and_b32 s2, s1, 0x3fc00
	s_mov_b32 s21, s3
	v_lshl_add_u64 v[176:177], v[118:119], 0, s[2:3]
	s_lshl_b64 s[38:39], s[20:21], 18
	v_lshl_add_u64 v[178:179], v[176:177], 0, s[38:39]
	global_load_dwordx4 v[128:131], v[178:179], off nt
	s_add_i32 s2, s20, 1
	s_lshl_b64 s[38:39], s[2:3], 18
	v_lshl_add_u64 v[182:183], v[176:177], 0, s[38:39]
	global_load_dwordx4 v[132:135], v[182:183], off nt
	s_add_i32 s2, s20, 2
	s_lshl_b64 s[38:39], s[2:3], 18
	v_lshl_add_u64 v[184:185], v[176:177], 0, s[38:39]
	global_load_dwordx4 v[136:139], v[184:185], off nt
	s_add_i32 s2, s20, 3
	s_lshl_b64 s[38:39], s[2:3], 18
	v_lshl_add_u64 v[186:187], v[176:177], 0, s[38:39]
	global_load_dwordx4 v[140:143], v[186:187], off nt
	s_add_i32 s2, s20, 4
	s_lshl_b64 s[38:39], s[2:3], 18
	v_lshl_add_u64 v[188:189], v[176:177], 0, s[38:39]
	global_load_dwordx4 v[144:147], v[188:189], off nt
	s_add_i32 s2, s20, 5
	s_lshl_b64 s[38:39], s[2:3], 18
	v_lshl_add_u64 v[190:191], v[176:177], 0, s[38:39]
	global_load_dwordx4 v[148:151], v[190:191], off nt
	s_add_i32 s2, s20, 6
	s_lshl_b64 s[38:39], s[2:3], 18
	v_lshl_add_u64 v[192:193], v[176:177], 0, s[38:39]
	global_load_dwordx4 v[152:155], v[192:193], off nt
	s_waitcnt vmcnt(6)
	v_pk_add_f32 v[98:99], v[130:131], 0 op_sel_hi:[1,0]
	v_pk_add_f32 v[96:97], v[128:129], 0 op_sel_hi:[1,0]
	s_waitcnt vmcnt(5)
	v_pk_add_f32 v[98:99], v[98:99], v[134:135]
	v_pk_add_f32 v[96:97], v[96:97], v[132:133]
	s_waitcnt vmcnt(4)
	v_pk_add_f32 v[98:99], v[98:99], v[138:139]
	v_pk_add_f32 v[96:97], v[96:97], v[136:137]
	s_waitcnt vmcnt(3)
	v_pk_add_f32 v[98:99], v[98:99], v[142:143]
	v_pk_add_f32 v[96:97], v[96:97], v[140:141]
	s_waitcnt vmcnt(2)
	v_pk_add_f32 v[98:99], v[98:99], v[146:147]
	v_pk_add_f32 v[96:97], v[96:97], v[144:145]
	s_waitcnt vmcnt(1)
	v_pk_add_f32 v[98:99], v[98:99], v[150:151]
	v_pk_add_f32 v[96:97], v[96:97], v[148:149]
	s_waitcnt vmcnt(0)
	v_pk_add_f32 v[98:99], v[98:99], v[154:155]
	v_pk_add_f32 v[96:97], v[96:97], v[152:153]
; template <int SRC, int EXTRA, bool OUT8 = false> ...
;     ...
;             const int p0 = pos[2 * row], p1 = pos[2 * row + 1]; const float w0 = gwt[2 * row], w1 = gwt[2 * row + 1]; const float hm = hp.stats[2 * row], hr = hp.stats[2 * row + 1];
; #pragma unroll
;             for (int j = 0; j < 4; ++j) { const f32x4 a = (*(const f32x4*)(hp.src + (size_t)row * 1024 + 256 * j + 4 * lane) - hm) * hr * *(const f32x4*)(hp.g + 256 * j + 4 * lane) + *(const f32x4*)(hp.b + 256 * j + 4 * lane);
;                 f32x4 y[2];
; #pragma unroll
;                 for (int q = 0; q < 2; ++q) { const int p = q ? p1 : p0; const int t = __builtin_amdgcn_readfirstlane(tailid[(p >> 8) * 4 + j]);
;                     if (t < 0) y[q] = *(const f32x4*)(ys + (size_t)p * 1024 + 256 * j + 4 * lane);
;                     else { f32x4 acc = (f32x4){0.f, 0.f, 0.f, 0.f};
; #pragma unroll
;                         for (int sl = 0; sl < 7; ++sl) acc = acc + *(const f32x4*)(part + ((size_t)(t * 7 + sl) * 256 + (p & 255)) * 256 + 4 * lane);
;                         y[q] = acc; } }
;                 v[j] = a * ALPHA + y[0] * w0 + y[1] * w1; }
.Lcomb_n12:
	v_readfirstlane_b32 s1, v175
	s_cmp_lt_i32 s1, 0
	s_cbranch_scc1 .Lcomb_n13
	s_mul_i32 s20, s1, 7
	s_lshl_b32 s1, s22, 10
	s_and_b32 s2, s1, 0x3fc00
	s_mov_b32 s21, s3
	v_lshl_add_u64 v[176:177], v[118:119], 0, s[2:3]
	s_lshl_b64 s[38:39], s[20:21], 18
	v_lshl_add_u64 v[178:179], v[176:177], 0, s[38:39]
	global_load_dwordx4 v[128:131], v[178:179], off nt
	s_add_i32 s2, s20, 1
	s_lshl_b64 s[38:39], s[2:3], 18
	v_lshl_add_u64 v[182:183], v[176:177], 0, s[38:39]
	global_load_dwordx4 v[132:135], v[182:183], off nt
	s_add_i32 s2, s20, 2
	s_lshl_b64 s[38:39], s[2:3], 18
	v_lshl_add_u64 v[184:185], v[176:177], 0, s[38:39]
	global_load_dwordx4 v[136:139], v[184:185], off nt
	s_add_i32 s2, s20, 3
	s_lshl_b64 s[38:39], s[2:3], 18
	v_lshl_add_u64 v[186:187], v[176:177], 0, s[38:39]
	global_load_dwordx4 v[140:143], v[186:187], off nt
	s_add_i32 s2, s20, 4
	s_lshl_b64 s[38:39], s[2:3], 18
	v_lshl_add_u64 v[188:189], v[176:177], 0, s[38:39]
	global_load_dwordx4 v[144:147], v[188:189], off nt
	s_add_i32 s2, s20, 5
	s_lshl_b64 s[38:39], s[2:3], 18
	v_lshl_add_u64 v[190:191], v[176:177], 0, s[38:39]
	global_load_dwordx4 v[148:151], v[190:191], off nt
	s_add_i32 s2, s20, 6
	s_lshl_b64 s[38:39], s[2:3], 18
	v_lshl_add_u64 v[192:193], v[176:177], 0, s[38:39]
	global_load_dwordx4 v[152:155], v[192:193], off nt
	s_waitcnt vmcnt(6)
	v_pk_add_f32 v[110:111], v[130:131], 0 op_sel_hi:[1,0]
	v_pk_add_f32 v[108:109], v[128:129], 0 op_sel_hi:[1,0]
	s_waitcnt vmcnt(5)
	v_pk_add_f32 v[110:111], v[110:111], v[134:135]
	v_pk_add_f32 v[108:109], v[108:109], v[132:133]
	s_waitcnt vmcnt(4)
	v_pk_add_f32 v[110:111], v[110:111], v[138:139]
	v_pk_add_f32 v[108:109], v[108:109], v[136:137]
	s_waitcnt vmcnt(3)
	v_pk_add_f32 v[110:111], v[110:111], v[142:143]
	v_pk_add_f32 v[108:109], v[108:109], v[140:141]
	s_waitcnt vmcnt(2)
	v_pk_add_f32 v[110:111], v[110:111], v[146:147]
	v_pk_add_f32 v[108:109], v[108:109], v[144:145]
	s_waitcnt vmcnt(1)
	v_pk_add_f32 v[110:111], v[110:111], v[150:151]
	v_pk_add_f32 v[108:109], v[108:109], v[148:149]
	s_waitcnt vmcnt(0)
	v_pk_add_f32 v[110:111], v[110:111], v[154:155]
	v_pk_add_f32 v[108:109], v[108:109], v[152:153]
.Lcomb_n13:
.LBB0_2278:
	v_sub_f32_e32 v83, v83, v124
	v_sub_f32_e32 v82, v82, v124
	v_sub_f32_e32 v81, v81, v124
	v_sub_f32_e32 v80, v80, v124
	v_pk_mul_f32 v[80:81], v[124:125], v[80:81] op_sel:[1,0]
	v_pk_mul_f32 v[82:83], v[124:125], v[82:83] op_sel:[1,0]
	v_sub_f32_e32 v43, v43, v124
	v_sub_f32_e32 v42, v42, v124
	v_sub_f32_e32 v41, v41, v124
	v_sub_f32_e32 v40, v40, v124
	v_pk_fma_f32 v[74:75], v[74:75], v[82:83], v[78:79]
	v_pk_fma_f32 v[72:73], v[72:73], v[80:81], v[76:77]
	v_pk_mul_f32 v[78:79], v[122:123], v[84:85] op_sel_hi:[0,1]
	v_pk_mul_f32 v[40:41], v[124:125], v[40:41] op_sel:[1,0]
	v_pk_mul_f32 v[42:43], v[124:125], v[42:43] op_sel:[1,0]
	v_pk_mul_f32 v[76:77], v[122:123], v[86:87] op_sel_hi:[0,1]
	v_pk_fma_f32 v[78:79], v[72:73], s[14:15], v[78:79] op_sel_hi:[1,0,1]
	v_pk_fma_f32 v[34:35], v[34:35], v[42:43], v[38:39]
	v_pk_fma_f32 v[32:33], v[32:33], v[40:41], v[36:37]
	v_pk_mul_f32 v[38:39], v[122:123], v[44:45] op_sel_hi:[0,1]
	v_pk_fma_f32 v[72:73], v[74:75], s[14:15], v[76:77] op_sel_hi:[1,0,1]
	v_pk_fma_f32 v[74:75], v[122:123], v[96:97], v[78:79] op_sel:[1,0,0]
	v_sub_f32_e32 v79, v101, v124
	v_sub_f32_e32 v78, v100, v124
	v_sub_f32_e32 v63, v63, v124
	v_sub_f32_e32 v62, v62, v124
	v_sub_f32_e32 v61, v61, v124
	v_sub_f32_e32 v60, v60, v124
	v_pk_mul_f32 v[36:37], v[122:123], v[46:47] op_sel_hi:[0,1]
	v_pk_fma_f32 v[32:33], v[32:33], s[14:15], v[38:39] op_sel_hi:[1,0,1]
	v_sub_f32_e32 v77, v103, v124
	v_sub_f32_e32 v76, v102, v124
	v_pk_mul_f32 v[60:61], v[124:125], v[60:61] op_sel:[1,0]
	v_pk_mul_f32 v[62:63], v[124:125], v[62:63] op_sel:[1,0]
	v_pk_fma_f32 v[34:35], v[34:35], s[14:15], v[36:37] op_sel_hi:[1,0,1]
	v_pk_fma_f32 v[38:39], v[122:123], v[48:49], v[32:33] op_sel:[1,0,0]
	v_pk_mul_f32 v[32:33], v[124:125], v[78:79] op_sel:[1,0]
	v_pk_fma_f32 v[54:55], v[54:55], v[62:63], v[58:59]
	v_pk_fma_f32 v[52:53], v[52:53], v[60:61], v[56:57]
	v_pk_mul_f32 v[56:57], v[122:123], v[66:67] op_sel_hi:[0,1]
	v_pk_mul_f32 v[58:59], v[122:123], v[64:65] op_sel_hi:[0,1]
	v_pk_fma_f32 v[36:37], v[122:123], v[50:51], v[34:35] op_sel:[1,0,0]
	v_pk_mul_f32 v[34:35], v[124:125], v[76:77] op_sel:[1,0]
	v_pk_fma_f32 v[32:33], v[88:89], v[32:33], v[92:93]
	v_pk_mul_f32 v[42:43], v[122:123], v[104:105] op_sel_hi:[0,1]
	v_pk_fma_f32 v[58:59], v[52:53], s[14:15], v[58:59] op_sel_hi:[1,0,1]
	v_pk_fma_f32 v[52:53], v[54:55], s[14:15], v[56:57] op_sel_hi:[1,0,1]
	v_pk_fma_f32 v[34:35], v[90:91], v[34:35], v[94:95]
	v_pk_mul_f32 v[40:41], v[122:123], v[106:107] op_sel_hi:[0,1]
	v_pk_fma_f32 v[42:43], v[32:33], s[14:15], v[42:43] op_sel_hi:[1,0,1]
	v_pk_fma_f32 v[52:53], v[122:123], v[70:71], v[52:53] op_sel:[1,0,0]
	v_pk_fma_f32 v[54:55], v[122:123], v[68:69], v[58:59] op_sel:[1,0,0]
	v_pk_fma_f32 v[32:33], v[34:35], s[14:15], v[40:41] op_sel_hi:[1,0,1]
	s_waitcnt vmcnt(0)
; __device__ __forceinline__ float shx(float v, int o) { const int l = lane_now(); return __int_as_float(__builtin_amdgcn_ds_bpermute((l ^ o) << 2, __float_as_int(v))); }
; __device__ __forceinline__ float wave_sum(float v) {
; #pragma unroll
;     for (int o = 1; o < 64; o <<= 1) v += shx(v, o);
;     return v;
; template <int SRC, int EXTRA, bool OUT8 = false> ...
;     ...
;         float s = 0.f;
; #pragma unroll
;         for (int j = 0; j < 4; ++j) s += (v[j].x + v[j].y) + (v[j].z + v[j].w);
;         const float mean = wave_sum(s) * (1.f / 1024.f); float s2 = 0.f;
; #pragma unroll
;         for (int j = 0; j < 4; ++j) { v[j] = v[j] - mean; s2 += (v[j].x * v[j].x + v[j].y * v[j].y) + (v[j].z * v[j].z + v[j].w * v[j].w); }
;         const float rstd = 1.f / sqrtf(wave_sum(s2) * (1.f / 1024.f) + LN_EPS);
;         if (stats && lane == 0) { stats[2 * row] = mean; stats[2 * row + 1] = rstd; }
; #pragma unroll
;         for (int j = 0; j < 4; ++j) { v[j] = v[j] * rstd * gv[j] + bv[j]; if (of32) *(f32x4*)(of32 + (size_t)row * 1024 + 256 * j + 4 * lane) = v[j];
	v_pk_fma_f32 v[34:35], v[122:123], v[108:109], v[42:43] op_sel:[1,0,0]
	v_pk_mov_b32 v[40:41], v[38:39], v[36:37] op_sel:[1,0]
	v_mov_b32_e32 v42, v38
	v_mov_b32_e32 v43, v37
	v_pk_add_f32 v[40:41], v[40:41], v[42:43]
	v_pk_mov_b32 v[42:43], v[54:55], v[52:53] op_sel:[1,0]
	v_mov_b32_e32 v44, v54
	v_mov_b32_e32 v45, v53
	v_pk_add_f32 v[42:43], v[42:43], v[44:45]
	v_pk_fma_f32 v[72:73], v[122:123], v[98:99], v[72:73] op_sel:[1,0,0]
	v_pk_fma_f32 v[32:33], v[122:123], v[110:111], v[32:33] op_sel:[1,0,0]
	v_add_f32_e32 v40, v40, v41
	v_pk_add_f32 v[42:43], v[42:43], v[42:43] op_sel:[0,1] op_sel_hi:[1,0]
	v_add_f32_e32 v40, 0, v40
	v_add_f32_e32 v44, v74, v75
	v_add_f32_e32 v46, v72, v73
	v_mov_b32_e32 v41, v34
	v_mov_b32_e32 v43, v35
	v_mov_b32_e32 v45, v32
	v_mov_b32_e32 v47, v33
	v_pk_add_f32 v[40:41], v[40:41], v[42:43]
	v_pk_add_f32 v[42:43], v[44:45], v[46:47]
	s_andn2_b64 vcc, exec, s[4:5]
	v_pk_add_f32 v[40:41], v[40:41], v[42:43]
	s_nop 0
	v_add_f32_e32 v40, v40, v41
	s_nop 0
	s_nop 1
	v_mov_b32_dpp v41, v40 quad_perm:[1,0,3,2] row_mask:0xf bank_mask:0xf
	v_add_f32_e32 v40, v40, v41
	s_nop 0
	s_nop 1
	v_mov_b32_dpp v41, v40 quad_perm:[2,3,0,1] row_mask:0xf bank_mask:0xf
	v_add_f32_e32 v40, v40, v41
	s_nop 0
	s_nop 1
	v_mov_b32_dpp v41, v40 row_shl:4 row_mask:0xf bank_mask:0x5
	v_mov_b32_dpp v41, v40 row_shr:4 row_mask:0xf bank_mask:0xa
	v_add_f32_e32 v40, v40, v41
	s_nop 0
	s_nop 1
	v_mov_b32_dpp v41, v40 row_ror:8 row_mask:0xf bank_mask:0xf
	v_add_f32_e32 v40, v40, v41
	s_nop 0
	v_mov_b32_e32 v41, v40
	v_mov_b32_e32 v200, v40
	s_nop 1
	v_permlane16_swap_b32_e32 v41, v200
	v_cndmask_b32_e64 v41, v200, v41, s[98:99]
	v_add_f32_e32 v40, v40, v41
	s_nop 0
	v_mov_b32_e32 v41, v40
	v_mov_b32_e32 v200, v40
	s_nop 1
	v_permlane32_swap_b32_e32 v41, v200
	v_cndmask_b32_e64 v41, v200, v41, s[100:101]
	v_add_f32_e32 v40, v40, v41
	v_fmamk_f32 v37, v40, 0xba800000, v37
	v_fmamk_f32 v39, v40, 0xba800000, v39
	v_fmac_f32_e32 v36, 0xba800000, v40
	v_fmac_f32_e32 v38, 0xba800000, v40
	v_mul_f32_e32 v41, v39, v39
	v_mul_f32_e32 v42, v37, v37
	v_fmac_f32_e32 v41, v38, v38
	v_fmac_f32_e32 v42, v36, v36
	v_fmamk_f32 v53, v40, 0xba800000, v53
	v_fmamk_f32 v55, v40, 0xba800000, v55
	v_add_f32_e32 v41, v41, v42
	v_fmac_f32_e32 v52, 0xba800000, v40
	v_fmac_f32_e32 v54, 0xba800000, v40
	v_mul_f32_e32 v42, v55, v55
	v_mul_f32_e32 v43, v53, v53
	v_fmac_f32_e32 v42, v54, v54
	v_fmac_f32_e32 v43, v52, v52
	v_add_f32_e32 v42, v42, v43
	v_fmamk_f32 v73, v40, 0xba800000, v73
	v_fmamk_f32 v75, v40, 0xba800000, v75
	v_add_f32_e32 v41, v41, v42
	v_fmac_f32_e32 v72, 0xba800000, v40
	v_fmac_f32_e32 v74, 0xba800000, v40
	v_mul_f32_e32 v42, v75, v75
	v_mul_f32_e32 v43, v73, v73
	v_fmac_f32_e32 v42, v74, v74
	v_fmac_f32_e32 v43, v72, v72
	v_add_f32_e32 v42, v42, v43
	v_fmamk_f32 v33, v40, 0xba800000, v33
	v_fmamk_f32 v35, v40, 0xba800000, v35
	v_add_f32_e32 v41, v42, v41
	v_fmac_f32_e32 v32, 0xba800000, v40
	v_fmac_f32_e32 v34, 0xba800000, v40
	v_mul_f32_e32 v40, v35, v35
	v_mul_f32_e32 v42, v33, v33
	v_fmac_f32_e32 v40, v34, v34
	v_fmac_f32_e32 v42, v32, v32
	v_add_f32_e32 v40, v40, v42
	v_add_f32_e32 v40, v40, v41
	s_nop 0
	s_nop 1
	v_mov_b32_dpp v41, v40 quad_perm:[1,0,3,2] row_mask:0xf bank_mask:0xf
	v_add_f32_e32 v40, v40, v41
	s_nop 0
	s_nop 1
	v_mov_b32_dpp v41, v40 quad_perm:[2,3,0,1] row_mask:0xf bank_mask:0xf
	v_add_f32_e32 v40, v40, v41
	s_nop 0
	s_nop 1
	v_mov_b32_dpp v41, v40 row_shl:4 row_mask:0xf bank_mask:0x5
	v_mov_b32_dpp v41, v40 row_shr:4 row_mask:0xf bank_mask:0xa
	v_add_f32_e32 v40, v40, v41
	s_nop 0
	s_nop 1
	v_mov_b32_dpp v41, v40 row_ror:8 row_mask:0xf bank_mask:0xf
	v_add_f32_e32 v40, v40, v41
	s_nop 0
	v_mov_b32_e32 v41, v40
	v_mov_b32_e32 v200, v40
	s_nop 1
	v_permlane16_swap_b32_e32 v41, v200
	v_cndmask_b32_e64 v41, v200, v41, s[98:99]
	v_add_f32_e32 v40, v40, v41
	s_nop 0
	v_mov_b32_e32 v41, v40
	v_mov_b32_e32 v200, v40
	s_nop 1
	v_permlane32_swap_b32_e32 v41, v200
	v_cndmask_b32_e64 v41, v200, v41, s[100:101]
	s_cbranch_vccnz .LBB0_2245
	v_add_f32_e32 v40, v40, v41
	v_fmamk_f32 v40, v40, 0x3a800000, v126
	v_mul_f32_e32 v41, 0x4f800000, v40
	v_cmp_gt_f32_e32 vcc, s33, v40
	s_nop 1
	v_cndmask_b32_e32 v40, v40, v41, vcc
	v_sqrt_f32_e32 v41, v40
	s_nop 0
	v_add_u32_e32 v42, -1, v41
	v_fma_f32 v44, -v42, v41, v40
	v_add_u32_e32 v43, 1, v41
	v_cmp_ge_f32_e64 s[0:1], 0, v44
	s_nop 1
	v_cndmask_b32_e64 v42, v41, v42, s[0:1]
	v_fma_f32 v41, -v43, v41, v40
	v_cmp_lt_f32_e64 s[0:1], 0, v41
	s_nop 1
	v_cndmask_b32_e64 v41, v42, v43, s[0:1]
	v_mul_f32_e32 v42, 0x37800000, v41
	v_cndmask_b32_e32 v41, v41, v42, vcc
	v_cmp_class_f32_e32 vcc, v40, v127
	s_nop 1
	v_cndmask_b32_e32 v42, v41, v40, vcc
	v_div_scale_f32 v43, s[0:1], v42, v42, 1.0
	v_rcp_f32_e32 v44, v43
	v_lshl_add_u64 v[40:41], s[12:13], 0, v[112:113]
	v_fma_f32 v45, -v43, v44, 1.0
	v_fmac_f32_e32 v44, v45, v44
	v_div_scale_f32 v45, vcc, 1.0, v42, 1.0
	v_mul_f32_e32 v46, v45, v44
	v_fma_f32 v47, -v43, v46, v45
	v_fmac_f32_e32 v46, v47, v44
	v_fma_f32 v43, -v43, v46, v45
	v_div_fmas_f32 v43, v43, v44, v46
	v_div_fixup_f32 v42, v43, v42, 1.0
	v_pk_mul_f32 v[44:45], v[38:39], v[42:43] op_sel_hi:[1,0]
	v_pk_mul_f32 v[36:37], v[36:37], v[42:43] op_sel_hi:[1,0]
	v_pk_mul_f32 v[32:33], v[32:33], v[42:43] op_sel_hi:[1,0]
	v_pk_fma_f32 v[38:39], v[2:3], v[36:37], v[6:7]
	v_pk_fma_f32 v[36:37], v[0:1], v[44:45], v[4:5]
	global_store_dwordx4 v[40:41], v[36:39], off nt
	s_nop 1
	v_pk_mul_f32 v[36:37], v[54:55], v[42:43] op_sel_hi:[1,0]
	v_pk_mul_f32 v[38:39], v[52:53], v[42:43] op_sel_hi:[1,0]
	v_pk_fma_f32 v[36:37], v[8:9], v[36:37], v[16:17]
	v_pk_fma_f32 v[38:39], v[10:11], v[38:39], v[18:19]
	global_store_dwordx4 v[40:41], v[36:39], off offset:1024 nt
	s_nop 1
	v_pk_mul_f32 v[36:37], v[74:75], v[42:43] op_sel_hi:[1,0]
	v_pk_mul_f32 v[38:39], v[72:73], v[42:43] op_sel_hi:[1,0]
	v_pk_fma_f32 v[36:37], v[12:13], v[36:37], v[20:21]
	v_pk_fma_f32 v[38:39], v[14:15], v[38:39], v[22:23]
	global_store_dwordx4 v[40:41], v[36:39], off offset:2048 nt
	s_nop 1
	v_pk_mul_f32 v[36:37], v[34:35], v[42:43] op_sel_hi:[1,0]
	v_pk_fma_f32 v[34:35], v[26:27], v[32:33], v[30:31]
	v_pk_fma_f32 v[32:33], v[24:25], v[36:37], v[28:29]
	global_store_dwordx4 v[40:41], v[32:35], off offset:3072 nt
	s_branch .LBB0_2245
